# phase k1: half of the workgroups (id bit 3) run attention before the LRU pass, so bandwidth-bound attention loads overlap the other half's VALU-bound LRU sweeps
# baseline (speedup 1.0000x reference)
; #define LAS __attribute__((address_space(3)))
; __global__ void __launch_bounds__(512, 2) fwd_kernel(Args args) {
;     extern __shared__ __attribute__((aligned(16))) unsigned char lds_raw[];
;     LAS unsigned char* lds = (LAS unsigned char*)lds_raw;
;     {
;         LAS unsigned long long* pt = (LAS unsigned long long*)(lds + 131072);
;         if (threadIdx.x == 0) {
; #pragma unroll
;             for (int i = 0; i < 19; ++i) pt[i] = (unsigned long long)args.in[i];
;             pt[19] = (unsigned long long)args.out; pt[20] = (unsigned long long)args.ws;
;         }
;         if (threadIdx.x == 32) { ((LAS unsigned*)(lds + 131072 + 512))[0] = 0u; ((LAS unsigned*)(lds + 131072 + 512))[1] = 0u; }
_Z10fwd_kernel4Args:
	s_mov_b32 s32, 0
	v_and_b32_e32 v188, 0x3ff, v0
	v_cmp_eq_u32_e64 s[4:5], 0, v188
	s_mov_b64 s[20:21], exec
	s_nop 0
	v_writelane_b32 v252, s4, 0
	s_nop 1
	v_writelane_b32 v252, s5, 1
	s_and_b64 s[4:5], s[20:21], s[4:5]
	s_mov_b64 exec, s[4:5]
	s_cbranch_execz .LBB0_2
	s_load_dwordx16 s[4:19], s[0:1], 0x0
	s_add_i32 s3, 0, 0x20000
	s_load_dwordx16 s[52:67], s[0:1], 0x40
	v_mov_b32_e32 v1, s3
	s_add_i32 s3, 0, 0x20010
	s_waitcnt lgkmcnt(0)
	v_mov_b32_e32 v2, s4
	v_mov_b32_e32 v3, s5
	v_mov_b32_e32 v4, s6
	v_mov_b32_e32 v5, s7
	ds_write_b128 v1, v[2:5]
	v_mov_b32_e32 v2, s8
	v_mov_b32_e32 v3, s9
	v_mov_b32_e32 v4, s10
	v_mov_b32_e32 v5, s11
	v_mov_b32_e32 v1, s3
	s_add_i32 s3, 0, 0x20020
	ds_write_b128 v1, v[2:5]
	v_mov_b32_e32 v2, s12
	v_mov_b32_e32 v3, s13
	v_mov_b32_e32 v4, s14
	v_mov_b32_e32 v5, s15
	v_mov_b32_e32 v1, s3
	s_add_i32 s3, 0, 0x20030
	ds_write_b128 v1, v[2:5]
	v_mov_b32_e32 v2, s16
	v_mov_b32_e32 v3, s17
	v_mov_b32_e32 v4, s18
	v_mov_b32_e32 v5, s19
	v_mov_b32_e32 v1, s3
	s_add_i32 s3, 0, 0x20040
	s_load_dwordx8 s[4:11], s[0:1], 0x80
	ds_write_b128 v1, v[2:5]
	v_mov_b32_e32 v2, s52
	v_mov_b32_e32 v3, s53
	v_mov_b32_e32 v4, s54
	v_mov_b32_e32 v5, s55
	v_mov_b32_e32 v1, s3
	s_add_i32 s3, 0, 0x20050
	ds_write_b128 v1, v[2:5]
	v_mov_b32_e32 v2, s56
	v_mov_b32_e32 v3, s57
	v_mov_b32_e32 v4, s58
	v_mov_b32_e32 v5, s59
	v_mov_b32_e32 v1, s3
	s_add_i32 s3, 0, 0x20060
	s_load_dwordx2 s[12:13], s[0:1], 0xa0
	ds_write_b128 v1, v[2:5]
	v_mov_b32_e32 v2, s60
	v_mov_b32_e32 v3, s61
	v_mov_b32_e32 v4, s62
	v_mov_b32_e32 v5, s63
	v_mov_b32_e32 v1, s3
	s_add_i32 s3, 0, 0x20070
	ds_write_b128 v1, v[2:5]
	v_mov_b32_e32 v2, s64
	v_mov_b32_e32 v3, s65
	v_mov_b32_e32 v4, s66
	v_mov_b32_e32 v5, s67
	v_mov_b32_e32 v1, s3
	s_add_i32 s3, 0, 0x20080
	ds_write_b128 v1, v[2:5]
	s_waitcnt lgkmcnt(0)
	v_mov_b32_e32 v2, s4
	v_mov_b32_e32 v3, s5
	v_mov_b32_e32 v4, s6
	v_mov_b32_e32 v5, s7
	v_mov_b32_e32 v1, s3
	s_add_i32 s3, 0, 0x20090
	ds_write_b128 v1, v[2:5]
	v_mov_b32_e32 v2, s8
	v_mov_b32_e32 v3, s9
	v_mov_b32_e32 v4, s10
	v_mov_b32_e32 v5, s11
	v_mov_b32_e32 v1, s3
	s_add_i32 s3, 0, 0x200a0
	ds_write_b128 v1, v[2:5]
	v_mov_b32_e32 v1, s3
	v_mov_b64_e32 v[2:3], s[12:13]
	ds_write_b64 v1, v[2:3]

; #define GAS __attribute__((address_space(1)))
; #define ARGP(i) ((const float*)(GAS const float*)ldsptr(lds, (i)))
; __global__ void __launch_bounds__(512, 2) fwd_kernel(Args args) {
;     ...
;         int tid = threadIdx.x; asm volatile("" : "+v"(tid));
;         const int lane = tid & 63, wave = __builtin_amdgcn_readfirstlane(tid >> 6);
;         const int G = gridDim.x, gw = blockIdx.x * 8 + wave, NGW = G * 8;
;         unsigned char* ws = (unsigned char*)(GAS unsigned char*)ldsptr(lds, 20);
;         bf16_t* const WIN = (bf16_t*)(ws + WS_WIN); bf16_t* const WAO = (bf16_t*)(ws + WS_WAO); bf16_t* const WRO = (bf16_t*)(ws + WS_WRO); bf16_t* const WOUT = (bf16_t*)(ws + WS_WOUT);
;         bf16_t* const W1 = (bf16_t*)(ws + WS_W1); bf16_t* const W2 = (bf16_t*)(ws + WS_W2); bf16_t* const WL = (bf16_t*)(ws + WS_WL);
;         float* const SS = (float*)(ws + WS_SS); float* const LSUM = (float*)(ws + WS_LSUM); float* const LCAR = (float*)(ws + WS_LCAR); float* const LSE = (float*)(ws + WS_LSE);
;         bf16_t* const XN = (bf16_t*)(ws + WS_XN); bf16_t* const ATT = (bf16_t*)(ws + WS_ATT); bf16_t* const RNN = (bf16_t*)(ws + WS_RNN); bf16_t* const OG = (bf16_t*)(ws + WS_OG);
;         bf16_t* const MG = (bf16_t*)(ws + WS_MG); bf16_t* const X2B = (bf16_t*)(ws + WS_X2B); unsigned char* const G8 = ws + WS_G8; bf16_t* const Z = (bf16_t*)(ws + WS_Z); bf16_t* const HB = (bf16_t*)(ws + WS_Z);
;         if (EN(9) && p == 0) {
;             phase_weights(lds, ws, 0, gw, NGW, wave, lane); phase_weights(lds, ws, 1, gw, NGW, wave, lane);
;             phase_xnorm(ARGP(0), ARGP(3), XN, gw, NGW, lane);
;         } else {
;             const int ck = (p - 1) / NPH, k = (p - 1) % NPH;
;             const int S = ck < 2 ? 2048 : 4096;
;             const float* xin = ck < 2 ? ARGP(0) + (size_t)ck * CH * DM : ARGP(1);
;             float* out = (float*)ARGP(19) + (size_t)ck * CH * DM;
.Lk1_redispatch:
	s_ashr_i32 s0, s25, 1
	v_writelane_b32 v254, s0, 39
	v_readlane_b32 s0, v253, 34
	v_mov_b32_e32 v142, v188
	s_nop 0
	v_mov_b32_e32 v1, s0
	s_waitcnt lgkmcnt(0)
	ds_read_b64 v[2:3], v1
	v_readfirstlane_b32 s0, v142
	s_ashr_i32 s0, s0, 6
	s_add_i32 s66, s0, s30
	v_writelane_b32 v254, s0, 40
	s_waitcnt lgkmcnt(0)
	v_readfirstlane_b32 s88, v2
	v_readfirstlane_b32 s89, v3
	s_add_u32 s74, s88, 0x100000
	s_addc_u32 s75, s89, 0
	s_add_u32 s0, s88, 0x2f00000
	s_addc_u32 s1, s89, 0
	v_writelane_b32 v254, s0, 41
	v_and_b32_e32 v202, 63, v142
	s_nop 0
	v_writelane_b32 v254, s1, 42
	s_add_u32 s0, s88, 0x3100000
	s_addc_u32 s1, s89, 0
	v_writelane_b32 v254, s0, 43
	s_nop 1
	v_writelane_b32 v254, s1, 44
	s_add_u32 s0, s88, 0x3700000
	s_addc_u32 s1, s89, 0
	s_add_u32 s82, s88, 0x3f00000
	v_writelane_b32 v254, s0, 45
	s_addc_u32 s83, s89, 0
	s_nop 0
	v_writelane_b32 v254, s1, 46
	s_add_u32 s0, s88, 0x5f00000
	s_addc_u32 s1, s89, 0
	v_writelane_b32 v254, s0, 47
	s_nop 1
	v_writelane_b32 v254, s1, 48
	s_add_u32 s0, s88, 0x7f00000
	s_addc_u32 s1, s89, 0
	s_add_u32 s70, s88, 0x8d00000
	v_writelane_b32 v254, s0, 49
	s_addc_u32 s71, s89, 0
	s_cmp_gt_u32 s25, 1
	v_writelane_b32 v254, s1, 50
	s_mov_b64 s[0:1], -1
	s_cbranch_scc0 .LBB0_299
	v_readlane_b32 s0, v254, 39
	s_cmp_lt_i32 s0, 19
	s_cselect_b64 s[4:5], -1, 0
	v_writelane_b32 v254, s4, 51
	s_cmp_gt_i32 s0, 18
	s_mov_b64 s[0:1], -1
	v_writelane_b32 v254, s5, 52
	s_cselect_b64 s[4:5], -1, 0
	v_writelane_b32 v254, s4, 53
	s_and_b64 vcc, exec, s[4:5]
	s_nop 0
	v_writelane_b32 v254, s5, 54
	s_cbranch_vccz .LBB0_17
	v_readlane_b32 s0, v253, 35
	s_nop 1
	v_mov_b32_e32 v1, s0
	ds_read_b64 v[2:3], v1
	s_mov_b64 s[0:1], 0
	s_waitcnt lgkmcnt(0)
	v_readfirstlane_b32 s8, v2
	v_readfirstlane_b32 s9, v3

; #define PG8_STAGE(bufoff, gbase, voff) do { _Pragma("unroll") for (int _i = 0; _i < 2; ++_i) \
;         __builtin_amdgcn_global_load_lds((const unsigned*)((const char*)(gbase) + (voff)[_i]), (PG8_LAS unsigned*)(lds + (bufoff) + ldsw + _i * 8192), 16, 0, 0); } while (0)
; #define PG8_LDA(dst, b, h) do { _Pragma("unroll") for (int m = 0; m < 4; ++m) _Pragma("unroll") for (int k = 0; k < 2; ++k) dst[m][k] = *(const PG8_LAS bf16x8*)(lds + PG8_SA(b, h) + aoff + m * 2048 + k * 1024); } while (0)
; #define PG8_LDB(dst, b, h) do { _Pragma("unroll") for (int n = 0; n < 2; ++n) _Pragma("unroll") for (int k = 0; k < 2; ++k) dst[n][k] = *(const PG8_LAS bf16x8*)(lds + PG8_SB(b, h) + boff + n * 2048 + k * 1024); } while (0)
; #define PG8_MMA(ai, bj, At, Bt) do { __builtin_amdgcn_s_setprio(1); _Pragma("unroll") for (int m = 0; m < 4; ++m) _Pragma("unroll") for (int n = 0; n < 2; ++n) _Pragma("unroll") for (int k = 0; k < 2; ++k) \
;         acc[ai][bj][m][n] = __builtin_amdgcn_mfma_f32_16x16x32_bf16(Bt[n][k], At[m][k], acc[ai][bj][m][n], 0, 0, 0); __builtin_amdgcn_s_setprio(0); } while (0)
; #define PG8_WAIT_V(n) asm volatile("s_waitcnt vmcnt(" #n ")" ::: "memory")
; #define PG8_BAR __builtin_amdgcn_s_barrier()
; template <class Epi, class Sched, bool ALIGN_EPI = false, bool SP2 = false>
; __device__ __forceinline__ void gemm_phase(PG8_LAS unsigned char* lds, const Gemm g, const Sched& S, const Epi& E) {
;     ...
;         for (int t = 0; t < nt; t += 2) {
;             const bool last = (t == nt - 2);
;             const char* a1 = cA + (size_t)(t + 1) * kstep;
;             const char* a2 = last ? nA : cA + (size_t)(t + 2) * kstep; const char* b2 = last ? nB : cB + (size_t)(t + 2) * kstep;
;             const char* a3 = a2 + kstep; const char* b3 = b2 + kstep;
;             if (last && has_next) S.a_ready(nxt);
;             if constexpr (SP2) {
;             PG8_LDB(B0, 0, 0); PG8_LDB(B1, 0, 1); PG8_SCHED; PG8_LDA(At, 0, 0); PG8_STAGE(PG8_SA(1, 1), a1 + hstep, voffA);
;             PG8_WAIT_V(8); PG8_WAIT_L(0); PG8_BAR; PG8_MMA(0, 0, At, B0); PG8_MMA(0, 1, At, B1); PG8_BAR; PG8_SCHED;
;             PG8_LDA(At, 0, 1); PG8_STAGE(PG8_SB(0, 0), b2, voffB); PG8_STAGE(PG8_SB(0, 1), b2 + hstep, voffB); PG8_STAGE(PG8_SA(0, 0), a2, voffA);
;             PG8_WAIT_V(8); PG8_WAIT_L(0); PG8_BAR; PG8_MMA(1, 0, At, B0); PG8_MMA(1, 1, At, B1); PG8_BAR; PG8_SCHED;
.LBB0_36:
	s_add_u32 s18, s58, 0xffe00080
	s_addc_u32 s19, s59, -1
	s_add_i32 s47, 0, 0x10000
	s_cmpk_eq_i32 s46, 0x7c
	s_cselect_b32 s63, s45, s19
	s_cselect_b32 s62, s73, s18
	v_add_u32_e32 v160, s47, v143
	s_cselect_b32 s19, s37, s79
	s_cselect_b32 s18, s84, s78
	s_add_i32 s80, 0, 0x14000
	ds_read_b128 v[156:159], v160
	ds_read_b128 v[164:167], v160 offset:1024
	ds_read_b128 v[168:171], v160 offset:2048
	ds_read_b128 v[172:175], v160 offset:3072
	v_add_u32_e32 v160, s80, v143
	ds_read_b128 v[176:179], v160
	ds_read_b128 v[180:183], v160 offset:1024
	ds_read_b128 v[184:187], v160 offset:2048
	ds_read_b128 v[204:207], v160 offset:3072
	v_lshl_add_u64 v[160:161], s[58:59], 0, v[152:153]
	s_add_i32 m0, s5, 0xc000
	ds_read_b128 v[208:211], v163
	ds_read_b128 v[212:215], v163 offset:1024
	ds_read_b128 v[216:219], v163 offset:2048
	ds_read_b128 v[220:223], v163 offset:3072
	ds_read_b128 v[224:227], v163 offset:4096
	ds_read_b128 v[228:231], v163 offset:5120
	ds_read_b128 v[232:235], v163 offset:6144
	ds_read_b128 v[236:239], v163 offset:7168
	global_load_lds_dwordx4 v[160:161], off
	v_lshl_add_u64 v[160:161], s[58:59], 0, v[154:155]
	s_add_i32 m0, s5, 0xe000
	s_nop 0
	global_load_lds_dwordx4 v[160:161], off
	s_nop 0
	s_nop 0
	s_waitcnt vmcnt(8)
	s_waitcnt lgkmcnt(0)
	s_barrier
	s_setprio 1
	v_mfma_f32_16x16x32_bf16 v[126:129], v[156:159], v[208:211], v[126:129]
	v_mfma_f32_16x16x32_bf16 v[122:125], v[168:171], v[208:211], v[122:125]
	v_mfma_f32_16x16x32_bf16 v[110:113], v[156:159], v[216:219], v[110:113]
	v_mfma_f32_16x16x32_bf16 v[106:109], v[168:171], v[216:219], v[106:109]
	v_mfma_f32_16x16x32_bf16 v[94:97], v[156:159], v[224:227], v[94:97]
	v_mfma_f32_16x16x32_bf16 v[90:93], v[168:171], v[224:227], v[90:93]
	v_mfma_f32_16x16x32_bf16 v[78:81], v[156:159], v[232:235], v[78:81]
	v_mfma_f32_16x16x32_bf16 v[74:77], v[168:171], v[232:235], v[74:77]
	s_setprio 0
	s_setprio 1
	v_mfma_f32_16x16x32_bf16 v[126:129], v[164:167], v[212:215], v[126:129]
	v_mfma_f32_16x16x32_bf16 v[122:125], v[172:175], v[212:215], v[122:125]
	v_mfma_f32_16x16x32_bf16 v[110:113], v[164:167], v[220:223], v[110:113]
	v_mfma_f32_16x16x32_bf16 v[106:109], v[172:175], v[220:223], v[106:109]
	v_mfma_f32_16x16x32_bf16 v[94:97], v[164:167], v[228:231], v[94:97]
	v_mfma_f32_16x16x32_bf16 v[90:93], v[172:175], v[228:231], v[90:93]
	v_mfma_f32_16x16x32_bf16 v[78:81], v[164:167], v[236:239], v[78:81]
	v_mfma_f32_16x16x32_bf16 v[74:77], v[172:175], v[236:239], v[74:77]
	s_setprio 0
	s_setprio 1
	v_mfma_f32_16x16x32_bf16 v[118:121], v[176:179], v[208:211], v[118:121]
	v_mfma_f32_16x16x32_bf16 v[114:117], v[184:187], v[208:211], v[114:117]
	v_mfma_f32_16x16x32_bf16 v[102:105], v[176:179], v[216:219], v[102:105]
	v_mfma_f32_16x16x32_bf16 v[98:101], v[184:187], v[216:219], v[98:101]
	v_mfma_f32_16x16x32_bf16 v[86:89], v[176:179], v[224:227], v[86:89]
	v_mfma_f32_16x16x32_bf16 v[82:85], v[184:187], v[224:227], v[82:85]
	v_mfma_f32_16x16x32_bf16 v[70:73], v[176:179], v[232:235], v[70:73]
	v_mfma_f32_16x16x32_bf16 v[66:69], v[184:187], v[232:235], v[66:69]
	s_setprio 0
	s_setprio 1
	v_mfma_f32_16x16x32_bf16 v[118:121], v[180:183], v[212:215], v[118:121]
	v_mfma_f32_16x16x32_bf16 v[114:117], v[204:207], v[212:215], v[114:117]
	v_mfma_f32_16x16x32_bf16 v[102:105], v[180:183], v[220:223], v[102:105]
	v_mfma_f32_16x16x32_bf16 v[98:101], v[204:207], v[220:223], v[98:101]
	v_mfma_f32_16x16x32_bf16 v[86:89], v[180:183], v[228:231], v[86:89]
	v_mfma_f32_16x16x32_bf16 v[82:85], v[204:207], v[228:231], v[82:85]
	v_mfma_f32_16x16x32_bf16 v[70:73], v[180:183], v[236:239], v[70:73]
	v_mfma_f32_16x16x32_bf16 v[66:69], v[204:207], v[236:239], v[66:69]
	s_setprio 0
	s_barrier
	s_add_i32 s47, s47, s4
	v_lshl_add_u64 v[160:161], s[18:19], 0, v[148:149]
	s_mov_b32 m0, s47
	ds_read_b128 v[208:211], v163 offset:16384
	ds_read_b128 v[212:215], v163 offset:17408
	ds_read_b128 v[216:219], v163 offset:18432
	ds_read_b128 v[220:223], v163 offset:19456
	ds_read_b128 v[224:227], v163 offset:20480
	ds_read_b128 v[228:231], v163 offset:21504
	ds_read_b128 v[232:235], v163 offset:22528
	ds_read_b128 v[236:239], v163 offset:23552
	global_load_lds_dwordx4 v[160:161], off
	s_add_i32 m0, s47, 0x2000
	s_add_u32 s76, s18, 0x200000
	v_lshl_add_u64 v[240:241], s[18:19], 0, v[144:145]
	s_addc_u32 s77, s19, 0
	s_add_i32 s47, s80, s4
	global_load_lds_dwordx4 v[240:241], off
	v_lshl_add_u64 v[242:243], s[76:77], 0, v[148:149]
	s_mov_b32 m0, s47
	v_lshl_add_u64 v[244:245], s[62:63], 0, v[146:147]
	global_load_lds_dwordx4 v[242:243], off
	v_lshl_add_u64 v[242:243], s[76:77], 0, v[144:145]
	s_add_i32 m0, s47, 0x2000
	s_nop 0
	global_load_lds_dwordx4 v[242:243], off
	v_lshl_add_u64 v[242:243], s[62:63], 0, v[150:151]
	s_mov_b32 m0, s5
	s_nop 0
	global_load_lds_dwordx4 v[242:243], off
	s_mov_b32 m0, s30
	s_nop 0
	global_load_lds_dwordx4 v[244:245], off
	s_waitcnt vmcnt(8)
	s_waitcnt lgkmcnt(0)
	s_barrier
; #define PG8_STAGE(bufoff, gbase, voff) do { _Pragma("unroll") for (int _i = 0; _i < 2; ++_i) \
;         __builtin_amdgcn_global_load_lds((const unsigned*)((const char*)(gbase) + (voff)[_i]), (PG8_LAS unsigned*)(lds + (bufoff) + ldsw + _i * 8192), 16, 0, 0); } while (0)
; #define PG8_LDA(dst, b, h) do { _Pragma("unroll") for (int m = 0; m < 4; ++m) _Pragma("unroll") for (int k = 0; k < 2; ++k) dst[m][k] = *(const PG8_LAS bf16x8*)(lds + PG8_SA(b, h) + aoff + m * 2048 + k * 1024); } while (0)
; #define PG8_LDB(dst, b, h) do { _Pragma("unroll") for (int n = 0; n < 2; ++n) _Pragma("unroll") for (int k = 0; k < 2; ++k) dst[n][k] = *(const PG8_LAS bf16x8*)(lds + PG8_SB(b, h) + boff + n * 2048 + k * 1024); } while (0)
; #define PG8_MMA(ai, bj, At, Bt) do { __builtin_amdgcn_s_setprio(1); _Pragma("unroll") for (int m = 0; m < 4; ++m) _Pragma("unroll") for (int n = 0; n < 2; ++n) _Pragma("unroll") for (int k = 0; k < 2; ++k) \
;         acc[ai][bj][m][n] = __builtin_amdgcn_mfma_f32_16x16x32_bf16(Bt[n][k], At[m][k], acc[ai][bj][m][n], 0, 0, 0); __builtin_amdgcn_s_setprio(0); } while (0)
; #define PG8_WAIT_V(n) asm volatile("s_waitcnt vmcnt(" #n ")" ::: "memory")
; #define PG8_WAIT_L(n) asm volatile("s_waitcnt lgkmcnt(" #n ")" ::: "memory")
; #define PG8_BAR __builtin_amdgcn_s_barrier()
; #define PG8_SCHED __builtin_amdgcn_sched_barrier(0)
; template <class Epi, class Sched, bool ALIGN_EPI = false, bool SP2 = false>
; __device__ __forceinline__ void gemm_phase(PG8_LAS unsigned char* lds, const Gemm g, const Sched& S, const Epi& E) {
;     ...
;             PG8_WAIT_V(8); PG8_WAIT_L(0); PG8_BAR; PG8_MMA(1, 0, At, B0); PG8_MMA(1, 1, At, B1); PG8_BAR; PG8_SCHED;
;             PG8_LDB(B0, 1, 0); PG8_LDB(B1, 1, 1); PG8_SCHED; PG8_LDA(At, 1, 0); PG8_STAGE(PG8_SA(0, 1), a2 + hstep, voffA);
;             PG8_WAIT_V(8); PG8_WAIT_L(0); PG8_BAR; PG8_MMA(0, 0, At, B0); PG8_MMA(0, 1, At, B1); PG8_BAR; PG8_SCHED;
	s_setprio 1
	v_mfma_f32_16x16x32_bf16 v[62:65], v[156:159], v[208:211], v[62:65]
	v_mfma_f32_16x16x32_bf16 v[58:61], v[168:171], v[208:211], v[58:61]
	v_mfma_f32_16x16x32_bf16 v[46:49], v[156:159], v[216:219], v[46:49]
	v_mfma_f32_16x16x32_bf16 v[42:45], v[168:171], v[216:219], v[42:45]
	v_mfma_f32_16x16x32_bf16 v[30:33], v[156:159], v[224:227], v[30:33]
	v_mfma_f32_16x16x32_bf16 v[26:29], v[168:171], v[224:227], v[26:29]
	v_mfma_f32_16x16x32_bf16 v[14:17], v[156:159], v[232:235], v[14:17]
	v_mfma_f32_16x16x32_bf16 v[10:13], v[168:171], v[232:235], v[10:13]
	s_setprio 0
	s_setprio 1
	v_mfma_f32_16x16x32_bf16 v[62:65], v[164:167], v[212:215], v[62:65]
	v_mfma_f32_16x16x32_bf16 v[58:61], v[172:175], v[212:215], v[58:61]
	v_mfma_f32_16x16x32_bf16 v[46:49], v[164:167], v[220:223], v[46:49]
	v_mfma_f32_16x16x32_bf16 v[42:45], v[172:175], v[220:223], v[42:45]
	v_mfma_f32_16x16x32_bf16 v[30:33], v[164:167], v[228:231], v[30:33]
	v_mfma_f32_16x16x32_bf16 v[26:29], v[172:175], v[228:231], v[26:29]
	v_mfma_f32_16x16x32_bf16 v[14:17], v[164:167], v[236:239], v[14:17]
	v_mfma_f32_16x16x32_bf16 v[10:13], v[172:175], v[236:239], v[10:13]
	s_setprio 0
	s_setprio 1
	v_mfma_f32_16x16x32_bf16 v[54:57], v[176:179], v[208:211], v[54:57]
	v_mfma_f32_16x16x32_bf16 v[50:53], v[184:187], v[208:211], v[50:53]
	v_mfma_f32_16x16x32_bf16 v[38:41], v[176:179], v[216:219], v[38:41]
	v_mfma_f32_16x16x32_bf16 v[34:37], v[184:187], v[216:219], v[34:37]
	v_mfma_f32_16x16x32_bf16 v[22:25], v[176:179], v[224:227], v[22:25]
	v_mfma_f32_16x16x32_bf16 v[18:21], v[184:187], v[224:227], v[18:21]
	v_mfma_f32_16x16x32_bf16 v[6:9], v[176:179], v[232:235], v[6:9]
	v_mfma_f32_16x16x32_bf16 v[2:5], v[184:187], v[232:235], v[2:5]
	s_setprio 0
	s_setprio 1
	v_mfma_f32_16x16x32_bf16 v[54:57], v[180:183], v[212:215], v[54:57]
	v_mfma_f32_16x16x32_bf16 v[50:53], v[204:207], v[212:215], v[50:53]
	v_mfma_f32_16x16x32_bf16 v[38:41], v[180:183], v[220:223], v[38:41]
	v_mfma_f32_16x16x32_bf16 v[34:37], v[204:207], v[220:223], v[34:37]
	v_mfma_f32_16x16x32_bf16 v[22:25], v[180:183], v[228:231], v[22:25]
	v_mfma_f32_16x16x32_bf16 v[18:21], v[204:207], v[228:231], v[18:21]
	v_mfma_f32_16x16x32_bf16 v[6:9], v[180:183], v[236:239], v[6:9]
	v_mfma_f32_16x16x32_bf16 v[2:5], v[204:207], v[236:239], v[2:5]
	s_setprio 0
	s_barrier
	s_add_i32 s47, 0, 0x18000
	s_add_i32 s76, 0, 0x1c000
	v_add_u32_e32 v172, s47, v143
	v_add_u32_e32 v203, s76, v143
	ds_read_b128 v[156:159], v172
	ds_read_b128 v[164:167], v172 offset:1024
	ds_read_b128 v[168:171], v172 offset:2048
	ds_read_b128 v[172:175], v172 offset:3072
	ds_read_b128 v[176:179], v203
	ds_read_b128 v[180:183], v203 offset:1024
	ds_read_b128 v[184:187], v203 offset:2048
	ds_read_b128 v[204:207], v203 offset:3072
	s_add_u32 s62, s62, 0x200000
	s_addc_u32 s63, s63, 0
	s_mov_b32 m0, s57
	v_lshl_add_u64 v[246:247], s[62:63], 0, v[150:151]
	ds_read_b128 v[208:211], v163 offset:32768
	ds_read_b128 v[212:215], v163 offset:33792
	ds_read_b128 v[216:219], v163 offset:34816
	ds_read_b128 v[220:223], v163 offset:35840
	ds_read_b128 v[224:227], v163 offset:36864
	ds_read_b128 v[228:231], v163 offset:37888
	ds_read_b128 v[232:235], v163 offset:38912
	ds_read_b128 v[236:239], v163 offset:39936
	global_load_lds_dwordx4 v[246:247], off
	v_lshl_add_u64 v[246:247], s[62:63], 0, v[146:147]
	s_mov_b32 m0, s67
	s_nop 0
	global_load_lds_dwordx4 v[246:247], off
	s_waitcnt vmcnt(8)
	s_waitcnt lgkmcnt(0)
	s_barrier
	s_setprio 1
	v_mfma_f32_16x16x32_bf16 v[126:129], v[156:159], v[208:211], v[126:129]
	v_mfma_f32_16x16x32_bf16 v[122:125], v[168:171], v[208:211], v[122:125]
	v_mfma_f32_16x16x32_bf16 v[110:113], v[156:159], v[216:219], v[110:113]
	v_mfma_f32_16x16x32_bf16 v[106:109], v[168:171], v[216:219], v[106:109]
	v_mfma_f32_16x16x32_bf16 v[94:97], v[156:159], v[224:227], v[94:97]
	v_mfma_f32_16x16x32_bf16 v[90:93], v[168:171], v[224:227], v[90:93]
	v_mfma_f32_16x16x32_bf16 v[78:81], v[156:159], v[232:235], v[78:81]
	v_mfma_f32_16x16x32_bf16 v[74:77], v[168:171], v[232:235], v[74:77]
	s_setprio 0
	s_setprio 1
	v_mfma_f32_16x16x32_bf16 v[126:129], v[164:167], v[212:215], v[126:129]
	v_mfma_f32_16x16x32_bf16 v[122:125], v[172:175], v[212:215], v[122:125]
	v_mfma_f32_16x16x32_bf16 v[110:113], v[164:167], v[220:223], v[110:113]
	v_mfma_f32_16x16x32_bf16 v[106:109], v[172:175], v[220:223], v[106:109]
	v_mfma_f32_16x16x32_bf16 v[94:97], v[164:167], v[228:231], v[94:97]
	v_mfma_f32_16x16x32_bf16 v[90:93], v[172:175], v[228:231], v[90:93]
	v_mfma_f32_16x16x32_bf16 v[78:81], v[164:167], v[236:239], v[78:81]
	v_mfma_f32_16x16x32_bf16 v[74:77], v[172:175], v[236:239], v[74:77]
	s_setprio 0
	s_setprio 1
	v_mfma_f32_16x16x32_bf16 v[118:121], v[176:179], v[208:211], v[118:121]
	v_mfma_f32_16x16x32_bf16 v[114:117], v[184:187], v[208:211], v[114:117]
	v_mfma_f32_16x16x32_bf16 v[102:105], v[176:179], v[216:219], v[102:105]
	v_mfma_f32_16x16x32_bf16 v[98:101], v[184:187], v[216:219], v[98:101]
	v_mfma_f32_16x16x32_bf16 v[86:89], v[176:179], v[224:227], v[86:89]
	v_mfma_f32_16x16x32_bf16 v[82:85], v[184:187], v[224:227], v[82:85]
	v_mfma_f32_16x16x32_bf16 v[70:73], v[176:179], v[232:235], v[70:73]
	v_mfma_f32_16x16x32_bf16 v[66:69], v[184:187], v[232:235], v[66:69]
	s_setprio 0
	s_setprio 1
	v_mfma_f32_16x16x32_bf16 v[118:121], v[180:183], v[212:215], v[118:121]
	v_mfma_f32_16x16x32_bf16 v[114:117], v[204:207], v[212:215], v[114:117]
	v_mfma_f32_16x16x32_bf16 v[102:105], v[180:183], v[220:223], v[102:105]
	v_mfma_f32_16x16x32_bf16 v[98:101], v[204:207], v[220:223], v[98:101]
	v_mfma_f32_16x16x32_bf16 v[86:89], v[180:183], v[228:231], v[86:89]
	v_mfma_f32_16x16x32_bf16 v[82:85], v[204:207], v[228:231], v[82:85]
	v_mfma_f32_16x16x32_bf16 v[70:73], v[180:183], v[236:239], v[70:73]
	v_mfma_f32_16x16x32_bf16 v[66:69], v[204:207], v[236:239], v[66:69]
	s_setprio 0
	s_barrier
; #define PG8_STAGE(bufoff, gbase, voff) do { _Pragma("unroll") for (int _i = 0; _i < 2; ++_i) \
;         __builtin_amdgcn_global_load_lds((const unsigned*)((const char*)(gbase) + (voff)[_i]), (PG8_LAS unsigned*)(lds + (bufoff) + ldsw + _i * 8192), 16, 0, 0); } while (0)
; #define PG8_LDA(dst, b, h) do { _Pragma("unroll") for (int m = 0; m < 4; ++m) _Pragma("unroll") for (int k = 0; k < 2; ++k) dst[m][k] = *(const PG8_LAS bf16x8*)(lds + PG8_SA(b, h) + aoff + m * 2048 + k * 1024); } while (0)
; #define PG8_WAIT_V(n) asm volatile("s_waitcnt vmcnt(" #n ")" ::: "memory")
; template <class Epi, class Sched, bool ALIGN_EPI = false, bool SP2 = false>
; __device__ __forceinline__ void gemm_phase(PG8_LAS unsigned char* lds, const Gemm g, const Sched& S, const Epi& E) {
;     ...
;             PG8_LDA(At, 1, 1); PG8_STAGE(PG8_SB(1, 0), b3, voffB); PG8_STAGE(PG8_SB(1, 1), b3 + hstep, voffB); PG8_STAGE(PG8_SA(1, 0), a3, voffA);
;             PG8_WAIT_V(8); PG8_WAIT_L(0); PG8_BAR; PG8_MMA(1, 0, At, B0); PG8_MMA(1, 1, At, B1); PG8_BAR; PG8_SCHED;
;             } else {
;             PG8_LDB(B0, 0, 0); PG8_SCHED; PG8_LDA(At, 0, 0); PG8_STAGE(PG8_SA(1, 1), a1 + hstep, voffA);
;             PG8_WAIT_L(8); PG8_BAR; PG8_WAIT_L(0); PG8_MMA(0, 0, At, B0); PG8_BAR; PG8_SCHED;
;             PG8_LDB(B1, 0, 1); PG8_STAGE(PG8_SB(0, 0), b2, voffB);
;             PG8_BAR; PG8_WAIT_L(0); PG8_MMA(0, 1, At, B1); PG8_BAR;
;             PG8_LDA(At, 0, 1); PG8_STAGE(PG8_SA(0, 0), a2, voffA);
;             PG8_BAR; PG8_WAIT_L(0); PG8_MMA(1, 0, At, B0); PG8_BAR; PG8_SCHED;
;             PG8_STAGE(PG8_SB(0, 1), b2 + hstep, voffB);
;             PG8_WAIT_V(6); PG8_BAR; PG8_MMA(1, 1, At, B1); PG8_BAR;
;             PG8_LDB(B0, 1, 0); PG8_SCHED; PG8_LDA(At, 1, 0); PG8_STAGE(PG8_SA(0, 1), a2 + hstep, voffA);
;             PG8_WAIT_L(8); PG8_BAR; PG8_WAIT_L(0); PG8_MMA(0, 0, At, B0); PG8_BAR; PG8_SCHED;
;             PG8_LDB(B1, 1, 1); PG8_STAGE(PG8_SB(1, 0), b3, voffB);
;             PG8_BAR; PG8_WAIT_L(0); PG8_MMA(0, 1, At, B1); PG8_BAR;
;             PG8_LDA(At, 1, 1); PG8_STAGE(PG8_SA(1, 0), a3, voffA);
;             PG8_BAR; PG8_WAIT_L(0); PG8_MMA(1, 0, At, B0); PG8_BAR; PG8_SCHED;
;             PG8_STAGE(PG8_SB(1, 1), b3 + hstep, voffB);
;             PG8_WAIT_V(6); PG8_BAR; PG8_MMA(1, 1, At, B1); PG8_BAR;
;             }
;         }
;         if constexpr (ALIGN_EPI) { if (wr == 0) PG8_BAR; }
	s_add_i32 s47, s47, s4
	v_lshl_add_u64 v[160:161], v[160:161], 0, s[68:69]
	s_mov_b32 m0, s47
	ds_read_b128 v[208:211], v163 offset:49152
	ds_read_b128 v[212:215], v163 offset:50176
	ds_read_b128 v[216:219], v163 offset:51200
	ds_read_b128 v[220:223], v163 offset:52224
	ds_read_b128 v[224:227], v163 offset:53248
	ds_read_b128 v[228:231], v163 offset:54272
	ds_read_b128 v[232:235], v163 offset:55296
	ds_read_b128 v[236:239], v163 offset:56320
	global_load_lds_dwordx4 v[160:161], off
	s_add_i32 m0, s47, 0x2000
	s_add_u32 s18, s18, 0x200080
	v_lshl_add_u64 v[160:161], v[240:241], 0, s[68:69]
	s_addc_u32 s19, s19, 0
	s_add_i32 s47, s76, s4
	global_load_lds_dwordx4 v[160:161], off
	v_lshl_add_u64 v[160:161], s[18:19], 0, v[148:149]
	s_mov_b32 m0, s47
	s_nop 0
	global_load_lds_dwordx4 v[160:161], off
	v_lshl_add_u64 v[160:161], s[18:19], 0, v[144:145]
	s_add_i32 m0, s47, 0x2000
	s_nop 0
	global_load_lds_dwordx4 v[160:161], off
	v_lshl_add_u64 v[160:161], v[242:243], 0, s[68:69]
	s_mov_b32 m0, s1
	s_nop 0
	global_load_lds_dwordx4 v[160:161], off
	v_lshl_add_u64 v[160:161], v[244:245], 0, s[68:69]
	s_mov_b32 m0, s60
	s_nop 0
	global_load_lds_dwordx4 v[160:161], off
	s_nop 0
	s_waitcnt vmcnt(8)
	s_waitcnt lgkmcnt(0)
	s_barrier
	s_setprio 1
	v_mfma_f32_16x16x32_bf16 v[62:65], v[156:159], v[208:211], v[62:65]
	v_mfma_f32_16x16x32_bf16 v[58:61], v[168:171], v[208:211], v[58:61]
	v_mfma_f32_16x16x32_bf16 v[46:49], v[156:159], v[216:219], v[46:49]
	v_mfma_f32_16x16x32_bf16 v[42:45], v[168:171], v[216:219], v[42:45]
	v_mfma_f32_16x16x32_bf16 v[30:33], v[156:159], v[224:227], v[30:33]
	v_mfma_f32_16x16x32_bf16 v[26:29], v[168:171], v[224:227], v[26:29]
	v_mfma_f32_16x16x32_bf16 v[14:17], v[156:159], v[232:235], v[14:17]
	v_mfma_f32_16x16x32_bf16 v[10:13], v[168:171], v[232:235], v[10:13]
	s_setprio 0
	s_setprio 1
	v_mfma_f32_16x16x32_bf16 v[62:65], v[164:167], v[212:215], v[62:65]
	v_mfma_f32_16x16x32_bf16 v[58:61], v[172:175], v[212:215], v[58:61]
	v_mfma_f32_16x16x32_bf16 v[46:49], v[164:167], v[220:223], v[46:49]
	v_mfma_f32_16x16x32_bf16 v[42:45], v[172:175], v[220:223], v[42:45]
	v_mfma_f32_16x16x32_bf16 v[30:33], v[164:167], v[228:231], v[30:33]
	v_mfma_f32_16x16x32_bf16 v[26:29], v[172:175], v[228:231], v[26:29]
	v_mfma_f32_16x16x32_bf16 v[14:17], v[164:167], v[236:239], v[14:17]
	v_mfma_f32_16x16x32_bf16 v[10:13], v[172:175], v[236:239], v[10:13]
	s_setprio 0
	s_setprio 1
	v_mfma_f32_16x16x32_bf16 v[54:57], v[176:179], v[208:211], v[54:57]
	v_mfma_f32_16x16x32_bf16 v[50:53], v[184:187], v[208:211], v[50:53]
	v_mfma_f32_16x16x32_bf16 v[38:41], v[176:179], v[216:219], v[38:41]
	v_mfma_f32_16x16x32_bf16 v[34:37], v[184:187], v[216:219], v[34:37]
	v_mfma_f32_16x16x32_bf16 v[22:25], v[176:179], v[224:227], v[22:25]
	v_mfma_f32_16x16x32_bf16 v[18:21], v[184:187], v[224:227], v[18:21]
	v_mfma_f32_16x16x32_bf16 v[6:9], v[176:179], v[232:235], v[6:9]
	v_mfma_f32_16x16x32_bf16 v[2:5], v[184:187], v[232:235], v[2:5]
	s_setprio 0
	s_setprio 1
	v_mfma_f32_16x16x32_bf16 v[54:57], v[180:183], v[212:215], v[54:57]
	v_mfma_f32_16x16x32_bf16 v[50:53], v[204:207], v[212:215], v[50:53]
	v_mfma_f32_16x16x32_bf16 v[38:41], v[180:183], v[220:223], v[38:41]
	v_mfma_f32_16x16x32_bf16 v[34:37], v[204:207], v[220:223], v[34:37]
	v_mfma_f32_16x16x32_bf16 v[22:25], v[180:183], v[228:231], v[22:25]
	v_mfma_f32_16x16x32_bf16 v[18:21], v[204:207], v[228:231], v[18:21]
	v_mfma_f32_16x16x32_bf16 v[6:9], v[180:183], v[236:239], v[6:9]
	v_mfma_f32_16x16x32_bf16 v[2:5], v[204:207], v[236:239], v[2:5]
	s_setprio 0
	s_barrier
	s_add_i32 s46, s46, 2
	s_add_u32 s58, s58, 0x100
	s_addc_u32 s59, s59, 0
	s_add_u32 s78, s78, 0x100
	s_addc_u32 s79, s79, 0
	s_cmpk_gt_u32 s46, 0x7d
	s_cbranch_scc0 .LBB0_36
	s_and_b64 vcc, exec, s[12:13]
	s_cbranch_vccz .LBB0_39
	s_barrier

; #define LAS __attribute__((address_space(3)))
; #define ARGP(i) ((const float*)(GAS const float*)ldsptr(lds, (i)))
; template <int PASS> __device__ __forceinline__ void phase_lru(LAS unsigned char* lds, const bf16_t* Z, const bf16_t* WL, float* LSUM, const float* LCAR, bf16_t* RNN,
;                                                               int S, int tid, int lane, int wave, int G) {
;     ...
;     const float* conv_w = ARGP(5); const float* conv_b = ARGP(6); const float* lba = ARGP(8); const float* lbx = ARGP(10); const float* lam = ARGP(11);
;     for (int item = blockIdx.x; item < 12 * 64; item += G) {
;         const int n = item >> 6, run = item & 63;
;         const int ch0 = n * 128 + wave * 16 + 4 * g4;
;         bf16x8 wf[4][4];
; #pragma unroll
;         for (int q = 0; q < 4; ++q)
; #pragma unroll
;             for (int s = 0; s < 4; ++s) wf[q][s] = *(const bf16x8*)(WL + ((size_t)((n * 4 + q) * 128 + wave * 16 + c)) * 128 + 32 * s + 8 * g4);
;         LAS f32x4* kc = (LAS f32x4*)(lds + LRU_KC + wave * 11264);
; #pragma unroll
;         for (int k = 0; k < 4; ++k) kc[(6 + k) * 64 + lane] = *(const f32x4*)(conv_w + k * LW + ch0);
;         kc[10 * 64 + lane] = *(const f32x4*)(conv_b + ch0);
; #pragma unroll
;         for (int d = 0; d < 2; ++d) { kc[(3 * d + 0) * 64 + lane] = *(const f32x4*)(lba + d * LW + ch0) * (-LOG2E); kc[(3 * d + 1) * 64 + lane] = *(const f32x4*)(lbx + d * LW + ch0) * (-LOG2E);
;             const f32x4 lv = *(const f32x4*)(lam + d * LW + ch0); f32x4 sp;
; #pragma unroll
;             for (int j = 0; j < 4; ++j) sp[j] = -8.0f * LOG2E * log1pf(expf(-lv[j]));
;             kc[(3 * d + 2) * 64 + lane] = sp; }
;     ...
;         u32x4 rawr[3];
;     ...
;         LRU_LOAD_RAW(run * 4)
; __global__ void __launch_bounds__(512, 2) fwd_kernel(Args args) {
;     ...
;             } else if (EN(1) && k == 1) {
;     ...
;                 phase_lru<0>(lds, Z, WL, LSUM, LCAR, RNN, S, tid, lane, wave, G);
;                 __syncthreads();
;     ...
;                 phase_attn(lds, Z, ARGP(2), OG, LSE, S, tid, lane, wave, G);
.LBB0_208:
	s_andn2_b64 vcc, exec, s[0:1]
	s_mov_b64 s[12:13], 0
	s_cbranch_vccnz .LBB0_254
	v_readlane_b32 s0, v254, 63
	s_cmp_gt_i32 s0, 0
	s_mov_b64 s[0:1], -1
	s_cbranch_scc0 .LBB0_252
	v_readlane_b32 s0, v253, 38
	v_lshrrev_b32_e32 v148, 4, v202
	v_and_b32_e32 v103, 15, v142
	v_mov_b32_e32 v1, s0
	s_waitcnt lgkmcnt(0)
	ds_read2_b64 v[2:5], v1 offset1:1
	v_readlane_b32 s0, v253, 39
	v_bfe_u32 v149, v142, 2, 2
	v_and_b32_e32 v143, 48, v142
	v_mov_b32_e32 v1, s0
	s_waitcnt lgkmcnt(0)
	v_readfirstlane_b32 s4, v2
	v_readfirstlane_b32 s5, v3
	ds_read_b64 v[2:3], v1
	v_readlane_b32 s0, v253, 40
	v_readfirstlane_b32 s12, v4
	v_readfirstlane_b32 s13, v5
	v_mov_b32_e32 v1, s0
	s_waitcnt lgkmcnt(0)
	v_readfirstlane_b32 s36, v2
	v_readfirstlane_b32 s37, v3
	ds_read_b128 v[2:5], v1
	v_readlane_b32 s0, v252, 9
	v_readlane_b32 s1, v252, 10
	s_andn2_b64 vcc, exec, s[0:1]
	v_or_b32_e32 v152, 4, v148
	s_waitcnt lgkmcnt(0)
	v_readfirstlane_b32 s94, v2
	v_readfirstlane_b32 s95, v3
	v_readfirstlane_b32 s96, v4
	v_readfirstlane_b32 s97, v5
	v_or_b32_e32 v151, 8, v148
	v_or_b32_e32 v150, 12, v148
	s_cbranch_vccnz .LBB0_239
	s_cmp_lg_u32 s32, 0
	s_cbranch_scc1 .Lk1_lru
	s_bitcmp1_b32 s2, 3
	s_cbranch_scc0 .Lk1_lru
	s_mov_b32 s32, 1
	s_branch .LBB0_239
.Lk1_lru:
	v_readlane_b32 s1, v254, 40
	s_lshl_b32 s0, s1, 4
	v_lshl_or_b32 v153, v148, 2, s0
	v_or_b32_e32 v154, s0, v103
	v_readlane_b32 s18, v254, 49
	s_mul_i32 s0, s1, 0x2c00
	v_and_b32_e32 v2, 48, v202
	v_mov_b32_e32 v3, v0
	v_readlane_b32 s19, v254, 50
	s_add_i32 s0, s0, 0
	v_lshrrev_b32_e32 v4, 5, v202
	v_lshlrev_b32_e32 v5, 2, v202
	v_lshl_add_u64 v[100:101], s[18:19], 0, v[2:3]
	v_lshl_add_u32 v155, v202, 4, s0
	v_lshlrev_b32_e32 v2, 3, v142
	v_lshl_or_b32 v4, s1, 1, v4
	v_and_b32_e32 v5, 12, v5
	s_movk_i32 s0, 0x430
	v_add_u32_e32 v7, 0x200, v142
	v_lshrrev_b32_e32 v1, 1, v202
	v_and_b32_e32 v102, 0x78, v2
	v_lshlrev_b32_e32 v2, 4, v142
	v_bitop3_b32 v4, v5, v4, v149 bitop3:0x36
	v_lshl_add_u32 v6, v103, 8, 0
	v_cmp_gt_i32_e64 s[42:43], s0, v142
	v_ashrrev_i32_e32 v157, 4, v7
	s_movk_i32 s0, 0x230
	v_add_u32_e32 v7, 0x400, v142
	v_and_b32_e32 v2, 0xf0, v2
	v_lshl_add_u32 v4, v4, 4, v6
	v_and_b32_e32 v1, 8, v1
	v_ashrrev_i32_e32 v156, 4, v142
	v_cmp_gt_i32_e64 s[44:45], s0, v142
	v_ashrrev_i32_e32 v158, 4, v7
	s_movk_i32 s0, 0x110
	v_or_b32_e32 v11, 48, v202
	v_bitop3_b32 v12, v5, v148, v149 bitop3:0x36
	v_bitop3_b32 v13, v5, v152, v149 bitop3:0x36
	v_bitop3_b32 v14, v5, v151, v149 bitop3:0x36
	v_bitop3_b32 v5, v5, v150, v149 bitop3:0x36
	v_add_u32_e32 v2, 0, v2
	v_lshl_add_u32 v3, v153, 1, 0
	v_mul_lo_u32 v7, v156, s0
	v_mul_lo_u32 v8, v157, s0
	v_mul_lo_u32 v9, v158, s0
	v_mul_u32_u24_e32 v10, 0x110, v103
	v_mul_u32_u24_e32 v11, 0x110, v11
	v_lshlrev_b32_e32 v12, 4, v12
	v_lshlrev_b32_e32 v13, 4, v13
	v_lshlrev_b32_e32 v14, 4, v14
	v_lshlrev_b32_e32 v5, 4, v5
	v_add_u32_e32 v166, v4, v1
	v_or_b32_e32 v1, v193, v143
	s_add_i32 s30, s62, -1
	v_cmp_eq_u32_e64 s[40:41], 0, v103
	v_cmp_gt_i32_e64 s[46:47], 48, v142
	v_lshl_or_b32 v104, v103, 4, v195
	v_mov_b32_e32 v105, v0
	v_add_u32_e32 v159, 62, v156
	v_add_u32_e32 v160, 62, v157
	v_add_u32_e32 v161, 62, v158
	v_add_u32_e32 v162, v2, v7
	v_add_u32_e32 v163, v2, v8
	v_add_u32_e32 v164, v2, v9
	v_add_u32_e32 v165, v3, v10
	v_add_u32_e32 v167, v3, v11
	v_lshlrev_b32_e32 v168, 2, v1
	v_add_u32_e32 v169, v6, v12
	v_add_u32_e32 v170, v6, v13
	v_add_u32_e32 v171, v6, v14
	v_add_u32_e32 v172, v6, v5
	v_readlane_b32 s54, v253, 31
	s_mov_b32 s57, s2
	s_branch .LBB0_213

; #define LAS __attribute__((address_space(3)))
; #define ARGP(i) ((const float*)(GAS const float*)ldsptr(lds, (i)))
; __device__ __forceinline__ void phase_attn(LAS unsigned char* lds, const bf16_t* Z, const float* rel_bias, bf16_t* OG, float* LSE, int S, int tid, int lane, int wave, int G) {
;     LAS float* tab = (LAS float*)(lds + ATT_TAB);
;     for (int e = tid; e < 12 * 192; e += 512) {
;         const int hh = e / 192, ri = e % 192, rel = ri - 95, gg = hh >> 2, dist = rel * (1 << (2 * gg));
;         const int n = dist < 0 ? -dist : dist; const float nf = (float)(n < 1 ? 1 : n);
;         int large = 8 + (int)(logf(nf / 8.0f) / logf(128.0f) * 8.0f); large = large < 15 ? large : 15;
;         const int bucket = (dist > 0 ? 16 : 0) + (n < 8 ? n : large);
;         tab[e] = (rel >= -64 && rel <= 64) ? rel_bias[bucket * 12 + hh] * LOG2E : -1e30f;
;     }
; __global__ void __launch_bounds__(512, 2) fwd_kernel(Args args) {
;     ...
;                 phase_attn(lds, Z, ARGP(2), OG, LSE, S, tid, lane, wave, G);
.LBB0_239:
	s_cmp_eq_u32 s32, 2
	s_cbranch_scc1 .Lk1_after_lru
	v_readlane_b32 s0, v253, 41
	s_barrier
	s_nop 0
	v_mov_b32_e32 v1, s0
	ds_read_b64 v[2:3], v1
	s_movk_i32 s4, 0x900
	v_cmp_gt_i32_e32 vcc, s4, v142
	s_waitcnt lgkmcnt(0)
	v_readfirstlane_b32 s0, v2
	v_readfirstlane_b32 s1, v3
	s_and_saveexec_b64 s[4:5], vcc
	v_readlane_b32 s96, v254, 14
	v_readlane_b32 s97, v254, 15
	s_movk_i32 s97, 0x171
	s_cbranch_execz .LBB0_244
	v_readlane_b32 s10, v253, 42
	v_mov_b32_e32 v2, v142
	s_nop 0
	v_lshl_add_u32 v1, v142, 2, s10
	s_mov_b64 s[10:11], 0
	s_branch .LBB0_242

; #define ARGP(i) ((const float*)(GAS const float*)ldsptr(lds, (i)))
; __global__ void __launch_bounds__(512, 2) fwd_kernel(Args args) {
;     ...
;                 phase_lru<0>(lds, Z, WL, LSUM, LCAR, RNN, S, tid, lane, wave, G);
;                 __syncthreads();
;     ...
;                 phase_attn(lds, Z, ARGP(2), OG, LSE, S, tid, lane, wave, G);
.LBB0_251:
	s_mov_b64 s[0:1], 0
	v_readlane_b32 s18, v254, 16
	s_mov_b32 s63, s79
	s_mov_b32 s67, s80
	s_cmp_eq_u32 s32, 1
	s_cbranch_scc0 .LBB0_252
	s_mov_b32 s32, 2
	s_branch .Lk1_redispatch
.Lk1_after_lru:
	s_mov_b32 s32, 0
	s_mov_b64 s[0:1], 0
	v_readlane_b32 s18, v254, 16
